# P2 token-shift loop: all four iterations' loads issued up front into rotating register sets (on top of the wave-uniform tanh mapping)
# baseline (speedup 1.0000x reference)
; __device__ __forceinline__ void phase_shift_cum(const Args& A, int gtid, int NGT, int gw, int lane) {
;     ...
;     for (int e = gtid; e < M * 64; e += NGT) {
;         const int m = e >> 6, c4 = (e & 63) * 4; const int t = m & (T - 1);
;         const f32x4 cur = *(const f32x4*)(WA + (size_t)m * 256 + c4);
;         const f32x4 prv = t ? *(const f32x4*)(WA + (size_t)(m - 1) * 256 + c4) : (f32x4){0.f, 0.f, 0.f, 0.f};
;         const f32x4 mm = *(const f32x4*)(mu + 4608 + c4);
.LBB0_286:
	s_mov_b64 s[4:5], s[34:35]
	v_lshl_add_u32 v15, s1, 9, v14
	s_mov_b32 s4, 0x80000
	v_cmp_gt_i32_e32 vcc, s4, v15
	s_and_saveexec_b64 s[4:5], vcc
	s_cbranch_execz .LBB0_311
	s_load_dwordx16 s[36:51], s[62:63], 0x0
	s_lshl_b32 s18, s12, 9
	s_add_u32 s6, s34, 0x17a00000
	s_addc_u32 s7, s35, 0
	s_add_u32 s8, s34, 0x22400000
	s_addc_u32 s9, s35, 0
	s_waitcnt lgkmcnt(0)
	s_mov_b64 s[24:25], s[44:45]
	s_mov_b64 s[26:27], s[46:47]
	s_add_u32 s10, s24, 0x4800
	v_lshlrev_b32_e32 v0, 2, v14
	s_addc_u32 s11, s25, 0
	v_lshl_add_u32 v16, s1, 11, v0
	s_lshl_b32 s19, s12, 11
	s_mov_b64 s[12:13], 0
	v_mov_b32_e32 v9, 0
	s_movk_i32 s20, 0x7f
	s_movk_i32 s21, 0x7fff
	s_mov_b32 s22, 0xffff0000
	s_mov_b32 s23, 0x3f200000
	s_mov_b32 s24, 0x3fb8aa3b
	s_mov_b32 s25, 0xc2ce8ed0
	s_mov_b32 s26, 0x42b17218
	v_mov_b32_e32 v17, 0x3ca908c9
	s_brev_b32 s27, -2
	s_mov_b32 s28, 0x7ffff
	v_mov_b32_e32 v18, 0x7f800000
	v_mov_b32_e32 v19, 1
	v_mov_b32_e32 v158, v15
	v_mov_b32_e32 v159, v16
	v_cmp_ge_i32_e32 vcc, s28, v158
	s_and_saveexec_b64 s[98:99], vcc
	s_cbranch_execz .Lp2pf_skip_p0
	v_lshrrev_b32_e32 v150, 6, v158
	v_bfe_u32 v152, v158, 5, 1
	v_bfe_u32 v153, v150, 2, 1
	v_and_b32_e32 v150, -5, v150
	v_lshl_or_b32 v150, v152, 2, v150
	v_ashrrev_i32_e32 v151, 31, v150
	v_and_b32_e32 v152, 31, v158
	v_lshl_or_b32 v152, v153, 5, v152
	v_lshlrev_b32_e32 v152, 2, v152
	v_lshlrev_b64 v[154:155], 10, v[150:151]
	v_lshl_add_u64 v[154:155], s[6:7], 0, v[154:155]
	v_lshlrev_b32_e32 v156, 2, v152
	v_mov_b32_e32 v157, 0
	v_lshl_add_u64 v[154:155], v[154:155], 0, v[156:157]
	global_load_dwordx4 v[100:103], v[154:155], off
	v_mov_b32_e32 v104, 0
	v_mov_b32_e32 v105, 0
	v_mov_b32_e32 v106, 0
	v_mov_b32_e32 v107, 0
	v_and_b32_e32 v153, 0xfff, v150
	v_cmp_ne_u32_e32 vcc, 0, v153
	s_and_saveexec_b64 s[100:101], vcc
	s_cbranch_execz .Lp2pf_noprv_p0
	global_load_dwordx4 v[104:107], v[154:155], off offset:-1024
.Lp2pf_noprv_p0:
	s_or_b64 exec, exec, s[100:101]
	global_load_dwordx4 v[108:111], v156, s[10:11]
.Lp2pf_skip_p0:
	s_or_b64 exec, exec, s[98:99]
	v_add_u32_e32 v158, s18, v158
	v_add_u32_e32 v159, s19, v159
	v_cmp_ge_i32_e32 vcc, s28, v158
	s_and_saveexec_b64 s[98:99], vcc
	s_cbranch_execz .Lp2pf_skip_p1
	v_lshrrev_b32_e32 v150, 6, v158
	v_bfe_u32 v152, v158, 5, 1
	v_bfe_u32 v153, v150, 2, 1
	v_and_b32_e32 v150, -5, v150
	v_lshl_or_b32 v150, v152, 2, v150
	v_ashrrev_i32_e32 v151, 31, v150
	v_and_b32_e32 v152, 31, v158
	v_lshl_or_b32 v152, v153, 5, v152
	v_lshlrev_b32_e32 v152, 2, v152
	v_lshlrev_b64 v[154:155], 10, v[150:151]
	v_lshl_add_u64 v[154:155], s[6:7], 0, v[154:155]
	v_lshlrev_b32_e32 v156, 2, v152
	v_mov_b32_e32 v157, 0
	v_lshl_add_u64 v[154:155], v[154:155], 0, v[156:157]
	global_load_dwordx4 v[112:115], v[154:155], off
	v_mov_b32_e32 v116, 0
	v_mov_b32_e32 v117, 0
	v_mov_b32_e32 v118, 0
	v_mov_b32_e32 v119, 0
	v_and_b32_e32 v153, 0xfff, v150
	v_cmp_ne_u32_e32 vcc, 0, v153
	s_and_saveexec_b64 s[100:101], vcc
	s_cbranch_execz .Lp2pf_noprv_p1
	global_load_dwordx4 v[116:119], v[154:155], off offset:-1024
.Lp2pf_noprv_p1:
	s_or_b64 exec, exec, s[100:101]
	global_load_dwordx4 v[120:123], v156, s[10:11]
.Lp2pf_skip_p1:
	s_or_b64 exec, exec, s[98:99]
	v_add_u32_e32 v158, s18, v158
	v_add_u32_e32 v159, s19, v159
	v_cmp_ge_i32_e32 vcc, s28, v158
	s_and_saveexec_b64 s[98:99], vcc
	s_cbranch_execz .Lp2pf_skip_p2
	v_lshrrev_b32_e32 v150, 6, v158
	v_bfe_u32 v152, v158, 5, 1
	v_bfe_u32 v153, v150, 2, 1
	v_and_b32_e32 v150, -5, v150
	v_lshl_or_b32 v150, v152, 2, v150
	v_ashrrev_i32_e32 v151, 31, v150
	v_and_b32_e32 v152, 31, v158
	v_lshl_or_b32 v152, v153, 5, v152
	v_lshlrev_b32_e32 v152, 2, v152
	v_lshlrev_b64 v[154:155], 10, v[150:151]
	v_lshl_add_u64 v[154:155], s[6:7], 0, v[154:155]
	v_lshlrev_b32_e32 v156, 2, v152
	v_mov_b32_e32 v157, 0
	v_lshl_add_u64 v[154:155], v[154:155], 0, v[156:157]
	global_load_dwordx4 v[124:127], v[154:155], off
	v_mov_b32_e32 v128, 0
	v_mov_b32_e32 v129, 0
	v_mov_b32_e32 v130, 0
	v_mov_b32_e32 v131, 0
	v_and_b32_e32 v153, 0xfff, v150
	v_cmp_ne_u32_e32 vcc, 0, v153
	s_and_saveexec_b64 s[100:101], vcc
	s_cbranch_execz .Lp2pf_noprv_p2
	global_load_dwordx4 v[128:131], v[154:155], off offset:-1024
.Lp2pf_noprv_p2:
	s_or_b64 exec, exec, s[100:101]
	global_load_dwordx4 v[132:135], v156, s[10:11]
.Lp2pf_skip_p2:
	s_or_b64 exec, exec, s[98:99]
	v_add_u32_e32 v158, s18, v158
	v_add_u32_e32 v159, s19, v159
	v_cmp_ge_i32_e32 vcc, s28, v158
	s_and_saveexec_b64 s[98:99], vcc
	s_cbranch_execz .Lp2pf_skip_p3
	v_lshrrev_b32_e32 v150, 6, v158
	v_bfe_u32 v152, v158, 5, 1
	v_bfe_u32 v153, v150, 2, 1
	v_and_b32_e32 v150, -5, v150
	v_lshl_or_b32 v150, v152, 2, v150
	v_ashrrev_i32_e32 v151, 31, v150
	v_and_b32_e32 v152, 31, v158
	v_lshl_or_b32 v152, v153, 5, v152
	v_lshlrev_b32_e32 v152, 2, v152
	v_lshlrev_b64 v[154:155], 10, v[150:151]
	v_lshl_add_u64 v[154:155], s[6:7], 0, v[154:155]
	v_lshlrev_b32_e32 v156, 2, v152
	v_mov_b32_e32 v157, 0
	v_lshl_add_u64 v[154:155], v[154:155], 0, v[156:157]
	global_load_dwordx4 v[136:139], v[154:155], off
	v_mov_b32_e32 v140, 0
	v_mov_b32_e32 v141, 0
	v_mov_b32_e32 v142, 0
	v_mov_b32_e32 v143, 0
	v_and_b32_e32 v153, 0xfff, v150
	v_cmp_ne_u32_e32 vcc, 0, v153
	s_and_saveexec_b64 s[100:101], vcc
	s_cbranch_execz .Lp2pf_noprv_p3
	global_load_dwordx4 v[140:143], v[154:155], off offset:-1024
.Lp2pf_noprv_p3:
	s_or_b64 exec, exec, s[100:101]
	global_load_dwordx4 v[144:147], v156, s[10:11]
.Lp2pf_skip_p3:
	s_or_b64 exec, exec, s[98:99]
	s_branch .LBB0_290

; __device__ __forceinline__ void phase_shift_cum(const Args& A, int gtid, int NGT, int gw, int lane) {
;     ...
;         const f32x4 cur = *(const f32x4*)(WA + (size_t)m * 256 + c4);
;         const f32x4 prv = t ? *(const f32x4*)(WA + (size_t)(m - 1) * 256 + c4) : (f32x4){0.f, 0.f, 0.f, 0.f};
;         const f32x4 mm = *(const f32x4*)(mu + 4608 + c4);
.LBB0_290:
	v_lshrrev_b32_e32 v10, 6, v15
	v_bfe_u32 v91, v15, 5, 1
	v_bfe_u32 v92, v10, 2, 1
	v_and_b32_e32 v10, -5, v10
	v_lshl_or_b32 v10, v91, 2, v10
	v_ashrrev_i32_e32 v11, 31, v10
	v_and_b32_e32 v20, 31, v15
	v_lshl_or_b32 v20, v92, 5, v20
	v_lshlrev_b32_e32 v20, 2, v20
	v_lshlrev_b64 v[0:1], 10, v[10:11]
	v_lshl_add_u64 v[0:1], s[6:7], 0, v[0:1]
	v_lshlrev_b32_e32 v8, 2, v20
	v_lshl_add_u64 v[12:13], v[0:1], 0, v[8:9]
	s_waitcnt vmcnt(0)
	v_mov_b64_e32 v[0:1], v[100:101]
	v_mov_b64_e32 v[2:3], v[102:103]
	v_mov_b64_e32 v[4:5], v[104:105]
	v_mov_b64_e32 v[6:7], v[106:107]
	v_mov_b64_e32 v[22:23], v[108:109]
	v_mov_b64_e32 v[24:25], v[110:111]
	v_mov_b64_e32 v[100:101], v[112:113]
	v_mov_b64_e32 v[102:103], v[114:115]
	v_mov_b64_e32 v[104:105], v[116:117]
	v_mov_b64_e32 v[106:107], v[118:119]
	v_mov_b64_e32 v[108:109], v[120:121]
	v_mov_b64_e32 v[110:111], v[122:123]
	v_mov_b64_e32 v[112:113], v[124:125]
	v_mov_b64_e32 v[114:115], v[126:127]
	v_mov_b64_e32 v[116:117], v[128:129]
	v_mov_b64_e32 v[118:119], v[130:131]
	v_mov_b64_e32 v[120:121], v[132:133]
	v_mov_b64_e32 v[122:123], v[134:135]
	v_mov_b64_e32 v[124:125], v[136:137]
	v_mov_b64_e32 v[126:127], v[138:139]
	v_mov_b64_e32 v[128:129], v[140:141]
	v_mov_b64_e32 v[130:131], v[142:143]
	v_mov_b64_e32 v[132:133], v[144:145]
	v_mov_b64_e32 v[134:135], v[146:147]
	v_mov_b32_e32 v158, s18
	v_lshl_add_u32 v158, v158, 2, v15
	v_mov_b32_e32 v159, s19
	v_lshl_add_u32 v159, v159, 2, v16
	v_cmp_ge_i32_e32 vcc, s28, v158
	s_and_saveexec_b64 s[98:99], vcc
	s_cbranch_execz .Lp2pf_skip_l
	v_lshrrev_b32_e32 v150, 6, v158
	v_bfe_u32 v152, v158, 5, 1
	v_bfe_u32 v153, v150, 2, 1
	v_and_b32_e32 v150, -5, v150
	v_lshl_or_b32 v150, v152, 2, v150
	v_ashrrev_i32_e32 v151, 31, v150
	v_and_b32_e32 v152, 31, v158
	v_lshl_or_b32 v152, v153, 5, v152
	v_lshlrev_b32_e32 v152, 2, v152
	v_lshlrev_b64 v[154:155], 10, v[150:151]
	v_lshl_add_u64 v[154:155], s[6:7], 0, v[154:155]
	v_lshlrev_b32_e32 v156, 2, v152
	v_mov_b32_e32 v157, 0
	v_lshl_add_u64 v[154:155], v[154:155], 0, v[156:157]
	global_load_dwordx4 v[136:139], v[154:155], off
	v_mov_b32_e32 v140, 0
	v_mov_b32_e32 v141, 0
	v_mov_b32_e32 v142, 0
	v_mov_b32_e32 v143, 0
	v_and_b32_e32 v153, 0xfff, v150
	v_cmp_ne_u32_e32 vcc, 0, v153
	s_and_saveexec_b64 s[100:101], vcc
	s_cbranch_execz .Lp2pf_noprv_l
	global_load_dwordx4 v[140:143], v[154:155], off offset:-1024

; __device__ __forceinline__ unsigned pk2(float lo, float hi) { return f2bf(lo) | (f2bf(hi) << 16); }
; __device__ __forceinline__ void phase_shift_cum(const Args& A, int gtid, int NGT, int gw, int lane) {
;     ...
;         const f32x4 cur = *(const f32x4*)(WA + (size_t)m * 256 + c4);
;         const f32x4 prv = t ? *(const f32x4*)(WA + (size_t)(m - 1) * 256 + c4) : (f32x4){0.f, 0.f, 0.f, 0.f};
;         const f32x4 mm = *(const f32x4*)(mu + 4608 + c4);
;         f32x4 v = cur + (prv - cur) * mm;
;         if (c4 < 128) { v.x = tanhf(v.x); v.y = tanhf(v.y); v.z = tanhf(v.z); v.w = tanhf(v.w);
;             *(v2u*)(A1 + (size_t)m * LORA + c4) = (v2u){pk2(v.x, v.y), pk2(v.z, v.w)}; }
;         else *(v2u*)(A2 + (size_t)m * LORA + (c4 - 128)) = (v2u){pk2(v.x, v.y), pk2(v.z, v.w)};
.Lp2pf_skip_l:
	s_or_b64 exec, exec, s[98:99]
	v_sub_f32_e32 v13, v5, v1
	v_sub_f32_e32 v12, v4, v0
	v_sub_f32_e32 v7, v7, v3
	v_sub_f32_e32 v6, v6, v2
	v_cmp_lt_u32_e32 vcc, s20, v20
	v_lshlrev_b64 v[4:5], 8, v[10:11]
	v_lshlrev_b32_e32 v8, 1, v20
	v_pk_fma_f32 v[2:3], v[6:7], v[24:25], v[2:3]
	v_pk_fma_f32 v[0:1], v[12:13], v[22:23], v[0:1]
	s_and_saveexec_b64 s[14:15], vcc
	s_xor_b64 s[14:15], exec, s[14:15]
	s_cbranch_execz .LBB0_294
	v_bfe_u32 v6, v0, 16, 1
	v_add3_u32 v0, v0, v6, s21
	v_bfe_u32 v6, v1, 16, 1
	v_lshrrev_b32_e32 v0, 16, v0
	v_add3_u32 v1, v1, v6, s21
	v_and_or_b32 v0, v1, s22, v0
	v_bfe_u32 v1, v2, 16, 1
	v_add3_u32 v1, v2, v1, s21
	v_bfe_u32 v2, v3, 16, 1
	v_lshrrev_b32_e32 v1, 16, v1
	v_add3_u32 v2, v3, v2, s21
	v_and_or_b32 v1, v2, s22, v1
	v_lshl_add_u64 v[2:3], s[34:35], 0, v[4:5]
	v_lshl_add_u64 v[2:3], v[2:3], 0, v[8:9]
	v_add_co_u32_e32 v2, vcc, 0x225ff000, v2
	s_nop 1
	v_addc_co_u32_e32 v3, vcc, 0, v3, vcc
	global_store_dwordx2 v[2:3], v[0:1], off offset:3840
